# attn0 prefetch: next step's Q also loaded at the step top into spare registers (copied after the wait)
# speedup vs baseline: 1.0084x; 1.0001x over previous
.La0_dma0:
	s_add_i32 vcc_lo, s75, s101
	s_mov_b32 vcc_hi, m0
	s_mov_b32 m0, vcc_lo
	s_nop 0
	global_load_lds_dwordx4 v[2:3], off
	s_mov_b32 m0, vcc_hi
	s_add_i32 s101, s101, 0x2000
	s_add_i32 s68, s101, 0xfffd8000
	s_cmp_ge_i32 s101, 0x28000
	s_cselect_b32 s101, s68, s101
	v_lshl_add_u64 v[2:3], v[2:3], 0, s[78:79]
	s_add_i32 s69, s69, -1
	s_cmp_lg_u32 s69, 0
	s_cbranch_scc1 .La0_dma0
	s_add_i32 s68, s94, s71
	s_lshl_b32 s98, s68, 12
	s_mov_b32 s99, 0
	v_lshl_add_u64 v[2:3], v[142:143], 0, s[98:99]
	global_load_dwordx4 v[64:67], v[2:3], off
	global_load_dwordx4 v[72:75], v[2:3], off offset:1024
	global_load_dwordx4 v[76:79], v[2:3], off offset:2048
	global_load_dwordx4 v[244:247], v[2:3], off offset:3072
	s_branch .LBB0_439

.La0_w1:
	v_mov_b32_e32 v92, v64
	v_mov_b32_e32 v93, v65
	v_mov_b32_e32 v94, v66
	v_mov_b32_e32 v95, v67
	v_mov_b32_e32 v88, v72
	v_mov_b32_e32 v89, v73
	v_mov_b32_e32 v90, v74
	v_mov_b32_e32 v91, v75
	v_mov_b32_e32 v84, v76
	v_mov_b32_e32 v85, v77
	v_mov_b32_e32 v86, v78
	v_mov_b32_e32 v87, v79
	v_mov_b32_e32 v80, v244
	v_mov_b32_e32 v81, v245
	v_mov_b32_e32 v82, v246
	v_mov_b32_e32 v83, v247
	s_waitcnt lgkmcnt(0)
	s_barrier
	s_and_b64 vcc, exec, s[88:89]
	s_cbranch_vccz .La0_nopv
	global_load_dword v154, v[146:147], off
	global_load_dwordx2 v[138:139], v[148:149], off
	global_load_dwordx2 v[136:137], v[148:149], off offset:16
	global_load_dwordx2 v[134:135], v[148:149], off offset:32
	global_load_dwordx2 v[132:133], v[148:149], off offset:48
	global_load_dwordx2 v[130:131], v[148:149], off offset:64
	global_load_dwordx2 v[128:129], v[148:149], off offset:80
	global_load_dwordx2 v[126:127], v[148:149], off offset:96
	global_load_dwordx2 v[124:125], v[148:149], off offset:112
	s_branch .La0_pvd

.La0_pvd:
	s_cmp_eq_u32 s95, 7
	s_cbranch_scc1 .La0_nopf
	s_add_i32 s68, s72, 8
	s_lshl_b32 s98, s68, 12
	s_mov_b32 s99, 0
	v_lshl_add_u64 v[2:3], v[142:143], 0, s[98:99]
	global_load_dwordx4 v[64:67], v[2:3], off
	global_load_dwordx4 v[72:75], v[2:3], off offset:1024
	global_load_dwordx4 v[76:79], v[2:3], off offset:2048
	global_load_dwordx4 v[244:247], v[2:3], off offset:3072
	s_sub_i32 s68, s72, s71
	s_add_i32 s68, s68, 8
	v_mov_b32_e32 v1, s68
	s_add_i32 s101, s84, 0x10000
	s_add_i32 s68, s101, 0xfffd8000
	s_cmp_ge_i32 s101, 0x28000
	s_cselect_b32 s101, s68, s101
	s_mov_b32 s69, 8
	v_mad_i64_i32 v[2:3], vcc, s78, v1, v[140:141]

.La0_have3:
	s_add_i32 s68, s100, 0x8000
	s_add_i32 s69, s68, 0xfffd8000
	s_cmp_ge_i32 s68, 0x28000
	s_cselect_b32 s68, s69, s68
	v_add_u32_e32 v158, s68, v152
	ds_read_b128 v[48:51], v158
	ds_read_b128 v[52:55], v158 offset:1024
	ds_read_b128 v[56:59], v158 offset:2048
	ds_read_b128 v[60:63], v158 offset:3072
	s_waitcnt lgkmcnt(3)
	v_mfma_f32_32x32x16_bf16 v[96:111], v[48:51], v[92:95], 0
	s_waitcnt lgkmcnt(2)
	v_mfma_f32_32x32x16_bf16 v[96:111], v[52:55], v[88:91], v[96:111]
	s_waitcnt lgkmcnt(1)
	v_mfma_f32_32x32x16_bf16 v[96:111], v[56:59], v[84:87], v[96:111]
	s_waitcnt lgkmcnt(0)
	v_mfma_f32_32x32x16_bf16 v[96:111], v[60:63], v[80:83], v[96:111]
	s_nop 7
	s_nop 4
	v_cndmask_b32_e64 v160, v160, v239, s[6:7]
	v_cndmask_b32_e64 v161, v161, v239, s[38:39]
	v_cndmask_b32_e64 v162, v162, v239, s[40:41]
	v_cndmask_b32_e64 v163, v163, v239, s[42:43]
	v_cndmask_b32_e64 v164, v164, v239, s[44:45]
	v_cndmask_b32_e64 v165, v165, v239, s[46:47]
	v_cndmask_b32_e64 v166, v166, v239, s[48:49]
	v_cndmask_b32_e64 v167, v167, v239, s[50:51]
	v_cndmask_b32_e64 v168, v168, v239, s[52:53]
	v_cndmask_b32_e64 v169, v169, v239, s[54:55]
	v_cndmask_b32_e64 v170, v170, v239, s[56:57]
	v_cndmask_b32_e64 v171, v171, v239, s[58:59]
	v_cndmask_b32_e64 v172, v172, v239, s[60:61]
	v_cndmask_b32_e64 v173, v173, v239, s[62:63]
	v_cndmask_b32_e64 v174, v174, v239, s[64:65]
	v_cndmask_b32_e64 v175, v175, v239, s[66:67]
	v_cndmask_b32_e64 v96, v96, v239, s[4:5]
	v_cndmask_b32_e64 v97, v239, v97, s[6:7]
	v_cndmask_b32_e64 v98, v98, v239, s[8:9]
	v_cndmask_b32_e64 v99, v99, v239, s[10:11]
	v_cndmask_b32_e64 v100, v100, v239, s[12:13]
	v_cndmask_b32_e64 v101, v101, v239, s[14:15]
	v_cndmask_b32_e64 v102, v102, v239, s[16:17]
	v_cndmask_b32_e64 v103, v103, v239, s[18:19]
	v_cndmask_b32_e64 v104, v104, v239, s[20:21]
	v_cndmask_b32_e64 v105, v105, v239, s[22:23]
	v_cndmask_b32_e64 v106, v106, v239, s[24:25]
	v_cndmask_b32_e64 v107, v107, v239, s[26:27]
	v_cndmask_b32_e64 v108, v108, v239, s[28:29]
	v_cndmask_b32_e64 v109, v109, v239, s[30:31]
	v_cndmask_b32_e64 v110, v110, v239, s[34:35]
	v_cndmask_b32_e64 v111, v111, v239, s[36:37]
	v_max3_f32 v12, v160, v161, v162
	v_max3_f32 v13, v163, v164, v165
	v_max3_f32 v14, v166, v167, v168
	v_max3_f32 v15, v169, v170, v171
	v_max3_f32 v12, v12, v172, v173
	v_max3_f32 v13, v13, v174, v175
	v_max3_f32 v14, v14, v176, v177
	v_max3_f32 v15, v15, v178, v179
	v_max3_f32 v12, v12, v180, v181
	v_max3_f32 v13, v13, v182, v183
	v_max3_f32 v14, v14, v184, v185
	v_max3_f32 v15, v15, v186, v187
	v_max3_f32 v12, v12, v188, v189
	v_max3_f32 v13, v13, v190, v191
	v_max3_f32 v14, v14, v192, v193
	v_max3_f32 v15, v15, v194, v195
	v_max3_f32 v12, v12, v196, v197
	v_max3_f32 v13, v13, v198, v199
	v_max3_f32 v14, v14, v200, v201
	v_max3_f32 v15, v15, v202, v203
	v_max3_f32 v12, v12, v204, v205
	v_max3_f32 v13, v13, v206, v207
	v_max3_f32 v14, v14, v208, v209
	v_max3_f32 v15, v15, v210, v211
	v_max3_f32 v12, v12, v212, v213
	v_max3_f32 v13, v13, v214, v215
	v_max3_f32 v14, v14, v216, v217
	v_max3_f32 v15, v15, v218, v219
	v_max3_f32 v12, v12, v220, v221
	v_max3_f32 v13, v13, v222, v223
	v_max3_f32 v14, v14, v96, v97
	v_max3_f32 v15, v15, v98, v99
	v_max3_f32 v12, v12, v100, v101
	v_max3_f32 v13, v13, v102, v103
	v_max3_f32 v14, v14, v104, v105
	v_max3_f32 v15, v15, v106, v107
	v_max3_f32 v12, v12, v108, v109
	v_max3_f32 v13, v13, v110, v111
	v_max3_f32 v12, v12, v13, v14
	v_max_f32_e32 v12, v12, v15
	ds_bpermute_b32 v13, v157, v12
	s_waitcnt lgkmcnt(0)
	v_max_f32_e32 v1, v12, v13
	v_sub_f32_e32 v160, v160, v1
	v_sub_f32_e32 v161, v161, v1
	v_sub_f32_e32 v162, v162, v1
	v_sub_f32_e32 v163, v163, v1
	v_sub_f32_e32 v164, v164, v1
	v_sub_f32_e32 v165, v165, v1
	v_sub_f32_e32 v166, v166, v1
	v_sub_f32_e32 v167, v167, v1
	v_sub_f32_e32 v168, v168, v1
	v_sub_f32_e32 v169, v169, v1
	v_sub_f32_e32 v170, v170, v1
	v_sub_f32_e32 v171, v171, v1
	v_sub_f32_e32 v172, v172, v1
	v_sub_f32_e32 v173, v173, v1
	v_sub_f32_e32 v174, v174, v1
	v_sub_f32_e32 v175, v175, v1
	v_sub_f32_e32 v176, v176, v1
	v_sub_f32_e32 v177, v177, v1
	v_sub_f32_e32 v178, v178, v1
	v_sub_f32_e32 v179, v179, v1
	v_sub_f32_e32 v180, v180, v1
	v_sub_f32_e32 v181, v181, v1
	v_sub_f32_e32 v182, v182, v1
	v_sub_f32_e32 v183, v183, v1
	v_sub_f32_e32 v184, v184, v1
	v_sub_f32_e32 v185, v185, v1
	v_sub_f32_e32 v186, v186, v1
	v_sub_f32_e32 v187, v187, v1
	v_sub_f32_e32 v188, v188, v1
	v_sub_f32_e32 v189, v189, v1
	v_sub_f32_e32 v190, v190, v1
	v_sub_f32_e32 v191, v191, v1
	v_sub_f32_e32 v192, v192, v1
	v_sub_f32_e32 v193, v193, v1
	v_sub_f32_e32 v194, v194, v1
	v_sub_f32_e32 v195, v195, v1
	v_sub_f32_e32 v196, v196, v1
	v_sub_f32_e32 v197, v197, v1
	v_sub_f32_e32 v198, v198, v1
	v_sub_f32_e32 v199, v199, v1
	v_sub_f32_e32 v200, v200, v1
	v_sub_f32_e32 v201, v201, v1
	v_sub_f32_e32 v202, v202, v1
	v_sub_f32_e32 v203, v203, v1
	v_sub_f32_e32 v204, v204, v1
	v_sub_f32_e32 v205, v205, v1
	v_sub_f32_e32 v206, v206, v1
	v_sub_f32_e32 v207, v207, v1
	v_sub_f32_e32 v208, v208, v1
	v_sub_f32_e32 v209, v209, v1
	v_sub_f32_e32 v210, v210, v1
	v_sub_f32_e32 v211, v211, v1
	v_sub_f32_e32 v212, v212, v1
	v_sub_f32_e32 v213, v213, v1
	v_sub_f32_e32 v214, v214, v1
	v_sub_f32_e32 v215, v215, v1
	v_sub_f32_e32 v216, v216, v1
	v_sub_f32_e32 v217, v217, v1
	v_sub_f32_e32 v218, v218, v1
	v_sub_f32_e32 v219, v219, v1
	v_sub_f32_e32 v220, v220, v1
	v_sub_f32_e32 v221, v221, v1
	v_sub_f32_e32 v222, v222, v1
	v_sub_f32_e32 v223, v223, v1
	v_sub_f32_e32 v96, v96, v1
	v_sub_f32_e32 v97, v97, v1
	v_sub_f32_e32 v98, v98, v1
	v_sub_f32_e32 v99, v99, v1
	v_sub_f32_e32 v100, v100, v1
	v_sub_f32_e32 v101, v101, v1
	v_sub_f32_e32 v102, v102, v1
	v_sub_f32_e32 v103, v103, v1
	v_sub_f32_e32 v104, v104, v1
	v_sub_f32_e32 v105, v105, v1
	v_sub_f32_e32 v106, v106, v1
	v_sub_f32_e32 v107, v107, v1
	v_sub_f32_e32 v108, v108, v1
	v_sub_f32_e32 v109, v109, v1
	v_sub_f32_e32 v110, v110, v1
	v_sub_f32_e32 v111, v111, v1
	v_exp_f32_e32 v160, v160
	v_exp_f32_e32 v161, v161
	v_exp_f32_e32 v162, v162
	v_exp_f32_e32 v163, v163
	v_exp_f32_e32 v164, v164
	v_exp_f32_e32 v165, v165
	v_exp_f32_e32 v166, v166
	v_exp_f32_e32 v167, v167
	v_exp_f32_e32 v168, v168
	v_exp_f32_e32 v169, v169
	v_exp_f32_e32 v170, v170
	v_exp_f32_e32 v171, v171
	v_exp_f32_e32 v172, v172
	v_exp_f32_e32 v173, v173
	v_exp_f32_e32 v174, v174
	v_exp_f32_e32 v175, v175
	v_exp_f32_e32 v176, v176
	v_exp_f32_e32 v177, v177
	v_exp_f32_e32 v178, v178
	v_exp_f32_e32 v179, v179
	v_exp_f32_e32 v180, v180
	v_exp_f32_e32 v181, v181
	v_exp_f32_e32 v182, v182
	v_exp_f32_e32 v183, v183
	v_exp_f32_e32 v184, v184
	v_exp_f32_e32 v185, v185
	v_exp_f32_e32 v186, v186
	v_exp_f32_e32 v187, v187
	v_exp_f32_e32 v188, v188
	v_exp_f32_e32 v189, v189
	v_exp_f32_e32 v190, v190
	v_exp_f32_e32 v191, v191
	v_exp_f32_e32 v192, v192
	v_exp_f32_e32 v193, v193
	v_exp_f32_e32 v194, v194
	v_exp_f32_e32 v195, v195
	v_exp_f32_e32 v196, v196
	v_exp_f32_e32 v197, v197
	v_exp_f32_e32 v198, v198
	v_exp_f32_e32 v199, v199
	v_exp_f32_e32 v200, v200
	v_exp_f32_e32 v201, v201
	v_exp_f32_e32 v202, v202
	v_exp_f32_e32 v203, v203
	v_exp_f32_e32 v204, v204
	v_exp_f32_e32 v205, v205
	v_exp_f32_e32 v206, v206
	v_exp_f32_e32 v207, v207
	v_exp_f32_e32 v208, v208
	v_exp_f32_e32 v209, v209
	v_exp_f32_e32 v210, v210
	v_exp_f32_e32 v211, v211
	v_exp_f32_e32 v212, v212
	v_exp_f32_e32 v213, v213
	v_exp_f32_e32 v214, v214
	v_exp_f32_e32 v215, v215
	v_exp_f32_e32 v216, v216
	v_exp_f32_e32 v217, v217
	v_exp_f32_e32 v218, v218
	v_exp_f32_e32 v219, v219
	v_exp_f32_e32 v220, v220
	v_exp_f32_e32 v221, v221
	v_exp_f32_e32 v222, v222
	v_exp_f32_e32 v223, v223
	v_exp_f32_e32 v96, v96
	v_exp_f32_e32 v97, v97
	v_exp_f32_e32 v98, v98
	v_exp_f32_e32 v99, v99
	v_exp_f32_e32 v100, v100
	v_exp_f32_e32 v101, v101
	v_exp_f32_e32 v102, v102
	v_exp_f32_e32 v103, v103
	v_exp_f32_e32 v104, v104
	v_exp_f32_e32 v105, v105
	v_exp_f32_e32 v106, v106
	v_exp_f32_e32 v107, v107
	v_exp_f32_e32 v108, v108
	v_exp_f32_e32 v109, v109
	v_exp_f32_e32 v110, v110
	v_exp_f32_e32 v111, v111
	v_add_f32_e32 v12, v160, v161
	v_add_f32_e32 v13, v162, v163
	v_add_f32_e32 v14, v164, v165
	v_add_f32_e32 v15, v166, v167
	v_add_f32_e32 v12, v168, v12
	v_add_f32_e32 v13, v169, v13
	v_add_f32_e32 v14, v170, v14
	v_add_f32_e32 v15, v171, v15
	v_add_f32_e32 v12, v172, v12
	v_add_f32_e32 v13, v173, v13
	v_add_f32_e32 v14, v174, v14
	v_add_f32_e32 v15, v175, v15
	v_add_f32_e32 v12, v176, v12
	v_add_f32_e32 v13, v177, v13
	v_add_f32_e32 v14, v178, v14
	v_add_f32_e32 v15, v179, v15
	v_add_f32_e32 v12, v180, v12
	v_add_f32_e32 v13, v181, v13
	v_add_f32_e32 v14, v182, v14
	v_add_f32_e32 v15, v183, v15
	v_add_f32_e32 v12, v184, v12
	v_add_f32_e32 v13, v185, v13
	v_add_f32_e32 v14, v186, v14
	v_add_f32_e32 v15, v187, v15
	v_add_f32_e32 v12, v188, v12
	v_add_f32_e32 v13, v189, v13
	v_add_f32_e32 v14, v190, v14
	v_add_f32_e32 v15, v191, v15
	v_add_f32_e32 v12, v192, v12
	v_add_f32_e32 v13, v193, v13
	v_add_f32_e32 v14, v194, v14
	v_add_f32_e32 v15, v195, v15
	v_add_f32_e32 v12, v196, v12
	v_add_f32_e32 v13, v197, v13
	v_add_f32_e32 v14, v198, v14
	v_add_f32_e32 v15, v199, v15
	v_add_f32_e32 v12, v200, v12
	v_add_f32_e32 v13, v201, v13
	v_add_f32_e32 v14, v202, v14
	v_add_f32_e32 v15, v203, v15
	v_add_f32_e32 v12, v204, v12
	v_add_f32_e32 v13, v205, v13
	v_add_f32_e32 v14, v206, v14
	v_add_f32_e32 v15, v207, v15
	v_add_f32_e32 v12, v208, v12
	v_add_f32_e32 v13, v209, v13
	v_add_f32_e32 v14, v210, v14
	v_add_f32_e32 v15, v211, v15
	v_add_f32_e32 v12, v212, v12
	v_add_f32_e32 v13, v213, v13
	v_add_f32_e32 v14, v214, v14
	v_add_f32_e32 v15, v215, v15
	v_add_f32_e32 v12, v216, v12
	v_add_f32_e32 v13, v217, v13
	v_add_f32_e32 v14, v218, v14
	v_add_f32_e32 v15, v219, v15
	v_add_f32_e32 v12, v220, v12
	v_add_f32_e32 v13, v221, v13
	v_add_f32_e32 v14, v222, v14
	v_add_f32_e32 v15, v223, v15
	v_add_f32_e32 v12, v96, v12
	v_add_f32_e32 v13, v97, v13
	v_add_f32_e32 v14, v98, v14
	v_add_f32_e32 v15, v99, v15
	v_add_f32_e32 v12, v100, v12
	v_add_f32_e32 v13, v101, v13
	v_add_f32_e32 v14, v102, v14
	v_add_f32_e32 v15, v103, v15
	v_add_f32_e32 v12, v104, v12
	v_add_f32_e32 v13, v105, v13
	v_add_f32_e32 v14, v106, v14
	v_add_f32_e32 v15, v107, v15
	v_add_f32_e32 v12, v108, v12
	v_add_f32_e32 v13, v109, v13
	v_add_f32_e32 v14, v110, v14
	v_add_f32_e32 v15, v111, v15
	v_add_f32_e32 v12, v12, v13
	v_add_f32_e32 v14, v14, v15
	v_add_f32_e32 v6, v12, v14
	v_cvt_pk_bf16_f32 v160, v160, v161
	v_cvt_pk_bf16_f32 v161, v162, v163
	v_cvt_pk_bf16_f32 v162, v164, v165
	v_cvt_pk_bf16_f32 v163, v166, v167
	v_cvt_pk_bf16_f32 v164, v168, v169
	v_cvt_pk_bf16_f32 v165, v170, v171
	v_cvt_pk_bf16_f32 v166, v172, v173
	v_cvt_pk_bf16_f32 v167, v174, v175
	v_cvt_pk_bf16_f32 v176, v176, v177
	v_cvt_pk_bf16_f32 v177, v178, v179
	v_cvt_pk_bf16_f32 v178, v180, v181
	v_cvt_pk_bf16_f32 v179, v182, v183
	v_cvt_pk_bf16_f32 v180, v184, v185
	v_cvt_pk_bf16_f32 v181, v186, v187
	v_cvt_pk_bf16_f32 v182, v188, v189
	v_cvt_pk_bf16_f32 v183, v190, v191
	v_cvt_pk_bf16_f32 v192, v192, v193
	v_cvt_pk_bf16_f32 v193, v194, v195
	v_cvt_pk_bf16_f32 v194, v196, v197
	v_cvt_pk_bf16_f32 v195, v198, v199
	v_cvt_pk_bf16_f32 v196, v200, v201
	v_cvt_pk_bf16_f32 v197, v202, v203
	v_cvt_pk_bf16_f32 v198, v204, v205
	v_cvt_pk_bf16_f32 v199, v206, v207
	v_cvt_pk_bf16_f32 v208, v208, v209
	v_cvt_pk_bf16_f32 v209, v210, v211
	v_cvt_pk_bf16_f32 v210, v212, v213
	v_cvt_pk_bf16_f32 v211, v214, v215
	v_cvt_pk_bf16_f32 v212, v216, v217
	v_cvt_pk_bf16_f32 v213, v218, v219
	v_cvt_pk_bf16_f32 v214, v220, v221
	v_cvt_pk_bf16_f32 v215, v222, v223
	v_cvt_pk_bf16_f32 v96, v96, v97
	v_cvt_pk_bf16_f32 v97, v98, v99
	v_cvt_pk_bf16_f32 v98, v100, v101
	v_cvt_pk_bf16_f32 v99, v102, v103
	v_cvt_pk_bf16_f32 v100, v104, v105
	v_cvt_pk_bf16_f32 v101, v106, v107
	v_cvt_pk_bf16_f32 v102, v108, v109
	v_cvt_pk_bf16_f32 v103, v110, v111
	s_add_i32 s68, s100, 0x8000
	s_add_i32 s69, s68, 0xfffd8000
	s_cmp_ge_i32 s68, 0x28000
	s_cselect_b32 s68, s69, s68
	v_add_u32_e32 v158, s68, v152
	ds_read_b128 v[48:51], v158 offset:4096
	ds_read_b128 v[52:55], v158 offset:5120
	ds_read_b128 v[56:59], v158 offset:6144
	ds_read_b128 v[60:63], v158 offset:7168
	s_waitcnt lgkmcnt(3)
	v_mfma_f32_32x32x16_bf16 v[32:47], v[48:51], v[96:99], 0
	s_waitcnt lgkmcnt(1)
	v_mfma_f32_32x32x16_bf16 v[16:31], v[56:59], v[96:99], 0
	v_mfma_f32_32x32x16_bf16 v[32:47], v[52:55], v[100:103], v[32:47]
	s_waitcnt lgkmcnt(0)
	v_mfma_f32_32x32x16_bf16 v[16:31], v[60:63], v[100:103], v[16:31]
	s_cmp_lt_i32 s85, 4
	s_cbranch_scc1 .La0_pvskip0
	s_add_i32 s68, s100, 0x0
	s_add_i32 s69, s68, 0xfffd8000
	s_cmp_ge_i32 s68, 0x28000
	s_cselect_b32 s68, s69, s68
	v_add_u32_e32 v158, s68, v152
	ds_read_b128 v[224:227], v158 offset:4096
	ds_read_b128 v[228:231], v158 offset:5120
	ds_read_b128 v[2:5], v158 offset:6144
	ds_read_b128 v[8:11], v158 offset:7168
	s_waitcnt lgkmcnt(3)
	v_mfma_f32_32x32x16_bf16 v[32:47], v[224:227], v[160:163], v[32:47]
	s_waitcnt lgkmcnt(1)
	v_mfma_f32_32x32x16_bf16 v[16:31], v[2:5], v[160:163], v[16:31]
	v_mfma_f32_32x32x16_bf16 v[32:47], v[228:231], v[164:167], v[32:47]
	s_waitcnt lgkmcnt(0)
	v_mfma_f32_32x32x16_bf16 v[16:31], v[8:11], v[164:167], v[16:31]
